# in-proj/out GEMM K-loops restructured: single staging register set, both k-half fragment reads up front, LDS stores + next loads between MFMA groups
# speedup vs baseline: 1.0073x; 1.0027x over previous
; template <int TJ>
; DI void gemm_core(const u16* __restrict__ W, int ldw, const u16* __restrict__ X, int ldx, int K, f32x16 (&acc)[2][TJ], char* lds) {
;     ...
;   G_LOAD(wA, xA, 0);
;   G_LOAD(wB, xB, 1);
;   G_STORE(wA, xA, 0);
;   __syncthreads();
;   for (int kt = 0; kt < nk; kt += 2) {
;     if (kt + 2 < nk) G_LOAD(wA, xA, kt + 2);
;     G_COMPUTE(0);
;     G_STORE(wB, xB, 1);
;     __syncthreads();
;     if (kt + 3 < nk) G_LOAD(wB, xB, kt + 3);
;     G_COMPUTE(1);
;     if (kt + 2 < nk) G_STORE(wA, xA, 0);
;     __syncthreads();
;   }
.LBB0_425:
	s_add_i32 s37, s37, 2
	s_cmp_lt_u32 s37, 30
	s_cselect_b64 s[30:31], -1, 0
	s_cmp_gt_u32 s37, 29
	s_cselect_b64 s[0:1], -1, 0
	v_lshl_add_u64 v[188:189], v[184:185], 0, v[64:65]
	v_lshl_add_u64 v[186:187], v[182:183], 0, v[64:65]
	ds_read_b128 v[232:235], v220
	ds_read_b128 v[236:239], v221
	ds_read_b128 v[240:243], v222 offset:8192
	ds_read_b128 v[244:247], v223 offset:8192
	ds_read_b128 v[248:251], v224 offset:8192
	ds_read_b128 v[206:209], v225 offset:8192
	ds_read_b128 v[130:133], v226
	ds_read_b128 v[134:137], v227
	ds_read_b128 v[138:141], v228 offset:8192
	ds_read_b128 v[142:145], v229 offset:8192
	ds_read_b128 v[154:157], v230 offset:8192
	ds_read_b128 v[162:165], v231 offset:8192
	s_setprio 1
	s_waitcnt lgkmcnt(9)
	v_mfma_f32_32x32x16_bf16 v[114:129], v[232:235], v[240:243], v[114:129]
	s_waitcnt lgkmcnt(8)
	v_mfma_f32_32x32x16_bf16 v[82:97], v[232:235], v[244:247], v[82:97]
	s_waitcnt lgkmcnt(7)
	v_mfma_f32_32x32x16_bf16 v[48:63], v[232:235], v[248:251], v[48:63]
	s_waitcnt lgkmcnt(6)
	v_mfma_f32_32x32x16_bf16 v[16:31], v[232:235], v[206:209], v[16:31]
	v_mfma_f32_32x32x16_bf16 v[98:113], v[236:239], v[240:243], v[98:113]
	v_mfma_f32_32x32x16_bf16 v[66:81], v[236:239], v[244:247], v[66:81]
	v_mfma_f32_32x32x16_bf16 v[32:47], v[236:239], v[248:251], v[32:47]
	v_mfma_f32_32x32x16_bf16 v[0:15], v[236:239], v[206:209], v[0:15]
	s_setprio 0
	s_waitcnt vmcnt(0)
	ds_write_b128 v214, v[146:149] offset:24576
	ds_write_b128 v216, v[150:153] offset:24576
	ds_write_b128 v215, v[158:161] offset:32768
	ds_write_b128 v217, v[166:169] offset:32768
	ds_write_b128 v218, v[170:173] offset:32768
	ds_write_b128 v219, v[174:177] offset:32768
	s_and_b64 vcc, exec, s[0:1]
	s_cbranch_vccnz .Lgl_ip_skipA
	v_add_co_u32_e32 v146, vcc, 0x1dc20000, v188
	s_nop 1
	v_addc_co_u32_e32 v147, vcc, 0, v189, vcc
	v_add_co_u32_e32 v150, vcc, 0x1dc40000, v188
	s_nop 1
	v_addc_co_u32_e32 v151, vcc, 0, v189, vcc
	v_add_co_u32_e32 v158, vcc, 0x18920000, v186
	global_load_dwordx4 v[146:149], v[146:147], off offset:128
	s_nop 0
	global_load_dwordx4 v[150:153], v[150:151], off offset:128
	v_addc_co_u32_e32 v159, vcc, 0, v187, vcc
	v_add_co_u32_e32 v166, vcc, 0x18940000, v186
	s_nop 1
	v_addc_co_u32_e32 v167, vcc, 0, v187, vcc
	v_add_co_u32_e32 v170, vcc, 0x18960000, v186
	global_load_dwordx4 v[158:161], v[158:159], off offset:128
	s_nop 0
	global_load_dwordx4 v[166:169], v[166:167], off offset:128
	v_addc_co_u32_e32 v171, vcc, 0, v187, vcc
	v_add_co_u32_e32 v174, vcc, 0x18980000, v186
	s_nop 1
	v_addc_co_u32_e32 v175, vcc, 0, v187, vcc
	global_load_dwordx4 v[170:173], v[170:171], off offset:128
	s_nop 0
	global_load_dwordx4 v[174:177], v[174:175], off offset:128
.Lgl_ip_skipA:
	s_waitcnt lgkmcnt(6)
	s_setprio 1
	v_mfma_f32_32x32x16_bf16 v[114:129], v[130:133], v[138:141], v[114:129]
	v_mfma_f32_32x32x16_bf16 v[82:97], v[130:133], v[142:145], v[82:97]
	v_mfma_f32_32x32x16_bf16 v[48:63], v[130:133], v[154:157], v[48:63]
	v_mfma_f32_32x32x16_bf16 v[16:31], v[130:133], v[162:165], v[16:31]
	v_mfma_f32_32x32x16_bf16 v[98:113], v[134:137], v[138:141], v[98:113]
	v_mfma_f32_32x32x16_bf16 v[66:81], v[134:137], v[142:145], v[66:81]
	v_mfma_f32_32x32x16_bf16 v[32:47], v[134:137], v[154:157], v[32:47]
	v_mfma_f32_32x32x16_bf16 v[0:15], v[134:137], v[162:165], v[0:15]
	s_setprio 0
	s_waitcnt lgkmcnt(0)
	s_barrier
	ds_read_b128 v[232:235], v220 offset:24576
	ds_read_b128 v[236:239], v221 offset:24576
	ds_read_b128 v[240:243], v222 offset:32768
	ds_read_b128 v[244:247], v223 offset:32768
	ds_read_b128 v[248:251], v224 offset:32768
	ds_read_b128 v[206:209], v225 offset:32768
	ds_read_b128 v[130:133], v226 offset:24576
	ds_read_b128 v[134:137], v227 offset:24576
	ds_read_b128 v[138:141], v228 offset:32768
	ds_read_b128 v[142:145], v229 offset:32768
	ds_read_b128 v[154:157], v230 offset:32768
	ds_read_b128 v[162:165], v231 offset:32768
	s_setprio 1
	s_waitcnt lgkmcnt(9)
	v_mfma_f32_32x32x16_bf16 v[114:129], v[232:235], v[240:243], v[114:129]
	s_waitcnt lgkmcnt(8)
	v_mfma_f32_32x32x16_bf16 v[82:97], v[232:235], v[244:247], v[82:97]
	s_waitcnt lgkmcnt(7)
	v_mfma_f32_32x32x16_bf16 v[48:63], v[232:235], v[248:251], v[48:63]
	s_waitcnt lgkmcnt(6)
	v_mfma_f32_32x32x16_bf16 v[16:31], v[232:235], v[206:209], v[16:31]
	v_mfma_f32_32x32x16_bf16 v[98:113], v[236:239], v[240:243], v[98:113]
	v_mfma_f32_32x32x16_bf16 v[66:81], v[236:239], v[244:247], v[66:81]
	v_mfma_f32_32x32x16_bf16 v[32:47], v[236:239], v[248:251], v[32:47]
	v_mfma_f32_32x32x16_bf16 v[0:15], v[236:239], v[206:209], v[0:15]
	s_setprio 0
	s_and_b64 vcc, exec, s[0:1]
	s_cbranch_vccnz .Lgl_ip_lastB
	s_waitcnt vmcnt(0)
	ds_write_b128 v214, v[146:149]
	ds_write_b128 v216, v[150:153]
	ds_write_b128 v215, v[158:161] offset:8192
	ds_write_b128 v217, v[166:169] offset:8192
	ds_write_b128 v218, v[170:173] offset:8192
	ds_write_b128 v219, v[174:177] offset:8192
	v_add_co_u32_e32 v146, vcc, 0x1dc20000, v188
	s_nop 1
	v_addc_co_u32_e32 v147, vcc, 0, v189, vcc
	v_add_co_u32_e32 v150, vcc, 0x1dc40000, v188
	s_nop 1
	v_addc_co_u32_e32 v151, vcc, 0, v189, vcc
	v_add_co_u32_e32 v158, vcc, 0x18920000, v186
	global_load_dwordx4 v[146:149], v[146:147], off offset:192
	s_nop 0
	global_load_dwordx4 v[150:153], v[150:151], off offset:192
	v_addc_co_u32_e32 v159, vcc, 0, v187, vcc
	v_add_co_u32_e32 v166, vcc, 0x18940000, v186
	s_nop 1
	v_addc_co_u32_e32 v167, vcc, 0, v187, vcc
	v_add_co_u32_e32 v170, vcc, 0x18960000, v186
	global_load_dwordx4 v[158:161], v[158:159], off offset:192
	s_nop 0
	global_load_dwordx4 v[166:169], v[166:167], off offset:192
	v_addc_co_u32_e32 v171, vcc, 0, v187, vcc
	v_add_co_u32_e32 v174, vcc, 0x18980000, v186
	s_nop 1
	v_addc_co_u32_e32 v175, vcc, 0, v187, vcc
	global_load_dwordx4 v[170:173], v[170:171], off offset:192
	s_nop 0
	global_load_dwordx4 v[174:177], v[174:175], off offset:192
	s_waitcnt lgkmcnt(6)
	s_branch .Lgl_ip_m2
.Lgl_ip_lastB:
	s_waitcnt lgkmcnt(0)
.Lgl_ip_m2:
	s_setprio 1
	v_mfma_f32_32x32x16_bf16 v[114:129], v[130:133], v[138:141], v[114:129]
	v_mfma_f32_32x32x16_bf16 v[82:97], v[130:133], v[142:145], v[82:97]
	v_mfma_f32_32x32x16_bf16 v[48:63], v[130:133], v[154:157], v[48:63]
	v_mfma_f32_32x32x16_bf16 v[16:31], v[130:133], v[162:165], v[16:31]
	v_mfma_f32_32x32x16_bf16 v[98:113], v[134:137], v[138:141], v[98:113]
	v_mfma_f32_32x32x16_bf16 v[66:81], v[134:137], v[142:145], v[66:81]
	v_mfma_f32_32x32x16_bf16 v[32:47], v[134:137], v[154:157], v[32:47]
	v_mfma_f32_32x32x16_bf16 v[0:15], v[134:137], v[162:165], v[0:15]
	s_setprio 0
	s_branch .LBB0_424

; template <int TJ>
; DI void gemm_core(const u16* __restrict__ W, int ldw, const u16* __restrict__ X, int ldx, int K, f32x16 (&acc)[2][TJ], char* lds) {
;     ...
;   G_LOAD(wA, xA, 0);
;   G_LOAD(wB, xB, 1);
;   G_STORE(wA, xA, 0);
;   __syncthreads();
;   for (int kt = 0; kt < nk; kt += 2) {
;     if (kt + 2 < nk) G_LOAD(wA, xA, kt + 2);
;     G_COMPUTE(0);
;     G_STORE(wB, xB, 1);
;     __syncthreads();
;     if (kt + 3 < nk) G_LOAD(wB, xB, kt + 3);
;     G_COMPUTE(1);
;     if (kt + 2 < nk) G_STORE(wA, xA, 0);
;     __syncthreads();
;   }
.LBB0_481:
	s_add_i32 s39, s39, 2
	s_cmp_lt_u32 s39, 30
	s_cselect_b64 s[2:3], -1, 0
	s_cmp_gt_u32 s39, 29
	s_cselect_b64 s[0:1], -1, 0
	ds_read_b128 v[206:209], v189
	ds_read_b128 v[226:229], v214
	ds_read_b128 v[230:233], v215 offset:8192
	ds_read_b128 v[234:237], v216 offset:8192
	ds_read_b128 v[238:241], v217 offset:8192
	ds_read_b128 v[242:245], v218 offset:8192
	ds_read_b128 v[130:133], v219
	ds_read_b128 v[134:137], v220
	ds_read_b128 v[138:141], v221 offset:8192
	ds_read_b128 v[142:145], v222 offset:8192
	ds_read_b128 v[146:149], v223 offset:8192
	ds_read_b128 v[150:153], v224 offset:8192
	s_setprio 1
	s_waitcnt lgkmcnt(9)
	v_mfma_f32_32x32x16_bf16 v[114:129], v[206:209], v[230:233], v[114:129]
	s_waitcnt lgkmcnt(8)
	v_mfma_f32_32x32x16_bf16 v[82:97], v[206:209], v[234:237], v[82:97]
	s_waitcnt lgkmcnt(7)
	v_mfma_f32_32x32x16_bf16 v[48:63], v[206:209], v[238:241], v[48:63]
	s_waitcnt lgkmcnt(6)
	v_mfma_f32_32x32x16_bf16 v[16:31], v[206:209], v[242:245], v[16:31]
	v_mfma_f32_32x32x16_bf16 v[98:113], v[226:229], v[230:233], v[98:113]
	v_mfma_f32_32x32x16_bf16 v[66:81], v[226:229], v[234:237], v[66:81]
	v_mfma_f32_32x32x16_bf16 v[32:47], v[226:229], v[238:241], v[32:47]
	v_mfma_f32_32x32x16_bf16 v[0:15], v[226:229], v[242:245], v[0:15]
	s_setprio 0
	s_waitcnt vmcnt(0)
	ds_write_b128 v183, v[154:157] offset:24576
	ds_write_b128 v185, v[158:161] offset:24576
	ds_write_b128 v184, v[162:165] offset:32768
	ds_write_b128 v186, v[166:169] offset:32768
	ds_write_b128 v187, v[170:173] offset:32768
	ds_write_b128 v188, v[174:177] offset:32768
	s_and_b64 vcc, exec, s[0:1]
	s_cbranch_vccnz .Lgl_op_skipA
	v_lshl_add_u64 v[154:155], v[180:181], 0, v[64:65]
	v_add_co_u32_e32 v156, vcc, 0x1d920000, v154
	v_lshl_add_u64 v[170:171], v[178:179], 0, v[64:65]
	s_nop 0
	v_addc_co_u32_e32 v157, vcc, 0, v155, vcc
	v_add_co_u32_e32 v158, vcc, 0x1d940000, v154
	s_nop 1
	v_addc_co_u32_e32 v159, vcc, 0, v155, vcc
	v_add_co_u32_e32 v166, vcc, 0xb9000, v170
	global_load_dwordx4 v[154:157], v[156:157], off offset:128
	s_nop 0
	global_load_dwordx4 v[158:161], v[158:159], off offset:128
	v_addc_co_u32_e32 v167, vcc, 0, v171, vcc
	v_add_co_u32_e32 v172, vcc, 0x172000, v170
	global_load_dwordx4 v[162:165], v[170:171], off offset:128
	s_nop 0
	global_load_dwordx4 v[166:169], v[166:167], off offset:128
	v_addc_co_u32_e32 v173, vcc, 0, v171, vcc
	v_add_co_u32_e32 v174, vcc, 0x22b000, v170
	s_nop 1
	v_addc_co_u32_e32 v175, vcc, 0, v171, vcc
	global_load_dwordx4 v[170:173], v[172:173], off offset:128
	s_nop 0
	global_load_dwordx4 v[174:177], v[174:175], off offset:128
.Lgl_op_skipA:
	s_waitcnt lgkmcnt(6)
	s_setprio 1
	v_mfma_f32_32x32x16_bf16 v[114:129], v[130:133], v[138:141], v[114:129]
	v_mfma_f32_32x32x16_bf16 v[82:97], v[130:133], v[142:145], v[82:97]
	v_mfma_f32_32x32x16_bf16 v[48:63], v[130:133], v[146:149], v[48:63]
	v_mfma_f32_32x32x16_bf16 v[16:31], v[130:133], v[150:153], v[16:31]
	v_mfma_f32_32x32x16_bf16 v[98:113], v[134:137], v[138:141], v[98:113]
	v_mfma_f32_32x32x16_bf16 v[66:81], v[134:137], v[142:145], v[66:81]
	v_mfma_f32_32x32x16_bf16 v[32:47], v[134:137], v[146:149], v[32:47]
	v_mfma_f32_32x32x16_bf16 v[0:15], v[134:137], v[150:153], v[0:15]
	s_setprio 0
	s_waitcnt lgkmcnt(0)
	s_barrier
	ds_read_b128 v[206:209], v189 offset:24576
	ds_read_b128 v[226:229], v214 offset:24576
	ds_read_b128 v[230:233], v215 offset:32768
	ds_read_b128 v[234:237], v216 offset:32768
	ds_read_b128 v[238:241], v217 offset:32768
	ds_read_b128 v[242:245], v218 offset:32768
	ds_read_b128 v[130:133], v219 offset:24576
	ds_read_b128 v[134:137], v220 offset:24576
	ds_read_b128 v[138:141], v221 offset:32768
	ds_read_b128 v[142:145], v222 offset:32768
	ds_read_b128 v[146:149], v223 offset:32768
	ds_read_b128 v[150:153], v224 offset:32768
	s_setprio 1
	s_waitcnt lgkmcnt(9)
	v_mfma_f32_32x32x16_bf16 v[114:129], v[206:209], v[230:233], v[114:129]
	s_waitcnt lgkmcnt(8)
	v_mfma_f32_32x32x16_bf16 v[82:97], v[206:209], v[234:237], v[82:97]
	s_waitcnt lgkmcnt(7)
	v_mfma_f32_32x32x16_bf16 v[48:63], v[206:209], v[238:241], v[48:63]
	s_waitcnt lgkmcnt(6)
	v_mfma_f32_32x32x16_bf16 v[16:31], v[206:209], v[242:245], v[16:31]
	v_mfma_f32_32x32x16_bf16 v[98:113], v[226:229], v[230:233], v[98:113]
	v_mfma_f32_32x32x16_bf16 v[66:81], v[226:229], v[234:237], v[66:81]
	v_mfma_f32_32x32x16_bf16 v[32:47], v[226:229], v[238:241], v[32:47]
	v_mfma_f32_32x32x16_bf16 v[0:15], v[226:229], v[242:245], v[0:15]
	s_setprio 0
	s_and_b64 vcc, exec, s[0:1]
	s_cbranch_vccnz .Lgl_op_lastB
	s_waitcnt vmcnt(0)
	ds_write_b128 v183, v[154:157]
	ds_write_b128 v185, v[158:161]
	ds_write_b128 v184, v[162:165] offset:8192
	ds_write_b128 v186, v[166:169] offset:8192
	ds_write_b128 v187, v[170:173] offset:8192
	ds_write_b128 v188, v[174:177] offset:8192
	v_lshl_add_u64 v[154:155], v[180:181], 0, v[64:65]
	v_add_co_u32_e32 v156, vcc, 0x1d920000, v154
	v_lshl_add_u64 v[170:171], v[178:179], 0, v[64:65]
	s_nop 0
	v_addc_co_u32_e32 v157, vcc, 0, v155, vcc
	v_add_co_u32_e32 v158, vcc, 0x1d940000, v154
	s_nop 1
	v_addc_co_u32_e32 v159, vcc, 0, v155, vcc
	v_add_co_u32_e32 v166, vcc, 0xb9000, v170
	global_load_dwordx4 v[154:157], v[156:157], off offset:192
	s_nop 0
	global_load_dwordx4 v[158:161], v[158:159], off offset:192
	v_addc_co_u32_e32 v167, vcc, 0, v171, vcc
	v_add_co_u32_e32 v172, vcc, 0x172000, v170
	global_load_dwordx4 v[162:165], v[170:171], off offset:192
	s_nop 0
	global_load_dwordx4 v[166:169], v[166:167], off offset:192
	v_addc_co_u32_e32 v173, vcc, 0, v171, vcc
	v_add_co_u32_e32 v174, vcc, 0x22b000, v170
	s_nop 1
	v_addc_co_u32_e32 v175, vcc, 0, v171, vcc
	global_load_dwordx4 v[170:173], v[172:173], off offset:192
	s_nop 0
	global_load_dwordx4 v[174:177], v[174:175], off offset:192
	s_waitcnt lgkmcnt(6)
	s_branch .Lgl_op_m2

; template <int TJ>
; DI void gemm_core(const u16* __restrict__ W, int ldw, const u16* __restrict__ X, int ldx, int K, f32x16 (&acc)[2][TJ], char* lds) {
;     ...
;   G_LOAD(wA, xA, 0);
;   G_LOAD(wB, xB, 1);
;   G_STORE(wA, xA, 0);
;   __syncthreads();
;   for (int kt = 0; kt < nk; kt += 2) {
;     if (kt + 2 < nk) G_LOAD(wA, xA, kt + 2);
;     G_COMPUTE(0);
;     G_STORE(wB, xB, 1);
;     __syncthreads();
;     if (kt + 3 < nk) G_LOAD(wB, xB, kt + 3);
;     G_COMPUTE(1);
;     if (kt + 2 < nk) G_STORE(wA, xA, 0);
;     __syncthreads();
;   }
.Lgl_op_m2:
	s_setprio 1
	v_mfma_f32_32x32x16_bf16 v[114:129], v[130:133], v[138:141], v[114:129]
	v_mfma_f32_32x32x16_bf16 v[82:97], v[130:133], v[142:145], v[82:97]
	v_mfma_f32_32x32x16_bf16 v[48:63], v[130:133], v[146:149], v[48:63]
	v_mfma_f32_32x32x16_bf16 v[16:31], v[130:133], v[150:153], v[16:31]
	v_mfma_f32_32x32x16_bf16 v[98:113], v[134:137], v[138:141], v[98:113]
	v_mfma_f32_32x32x16_bf16 v[66:81], v[134:137], v[142:145], v[66:81]
	v_mfma_f32_32x32x16_bf16 v[32:47], v[134:137], v[146:149], v[32:47]
	v_mfma_f32_32x32x16_bf16 v[0:15], v[134:137], v[150:153], v[0:15]
	s_setprio 0
	s_branch .LBB0_480
